# norm phases: GLR-projection A-operand loads batched (16 in flight), next-row x loads prefetched one row ahead with counted vmcnt
# speedup vs baseline: 1.0026x; 1.0026x over previous
.LBB0_55:
	v_mbcnt_hi_u32_b32 v2, -1, v1
	v_and_b32_e32 v3, 64, v2
	v_add_u32_e32 v3, 64, v3
	v_xor_b32_e32 v4, 1, v2
	v_cmp_lt_i32_e32 vcc, v4, v3
	s_mov_b64 s[12:13], 0x1400
	s_ashr_i32 s9, s8, 31
	v_cndmask_b32_e32 v4, v2, v4, vcc
	v_lshlrev_b32_e32 v38, 2, v4
	v_xor_b32_e32 v4, 2, v2
	v_cmp_lt_i32_e32 vcc, v4, v3
	s_mov_b64 s[10:11], 0x1000
	v_mov_b32_e32 v44, 0x358637bd
	v_cndmask_b32_e32 v4, v2, v4, vcc
	v_lshlrev_b32_e32 v39, 2, v4
	v_xor_b32_e32 v4, 4, v2
	v_cmp_lt_i32_e32 vcc, v4, v3
	s_mov_b32 s14, s8
	s_nop 0
	v_cndmask_b32_e32 v4, v2, v4, vcc
	v_lshlrev_b32_e32 v40, 2, v4
	v_xor_b32_e32 v4, 8, v2
	v_cmp_lt_i32_e32 vcc, v4, v3
	s_nop 1
	v_cndmask_b32_e32 v4, v2, v4, vcc
	v_lshlrev_b32_e32 v41, 2, v4
	v_xor_b32_e32 v4, 16, v2
	v_cmp_lt_i32_e32 vcc, v4, v3
	s_nop 1
	v_cndmask_b32_e32 v4, v2, v4, vcc
	v_lshlrev_b32_e32 v42, 2, v4
	v_xor_b32_e32 v4, 32, v2
	v_cmp_lt_i32_e32 vcc, v4, v3
	v_mov_b32_e32 v3, 0
	s_nop 0
	v_cndmask_b32_e32 v2, v2, v4, vcc
	v_lshlrev_b32_e32 v43, 2, v2
	v_lshlrev_b32_e32 v2, 4, v37
	v_lshl_add_u64 v[22:23], s[54:55], 0, v[2:3]
	v_lshl_add_u64 v[26:27], v[22:23], 0, s[12:13]
	s_mov_b64 s[12:13], 0x1800
	v_lshl_add_u64 v[28:29], v[22:23], 0, s[12:13]
	s_mov_b64 s[12:13], 0x1c00
	v_lshl_add_u64 v[30:31], v[22:23], 0, s[12:13]
	s_lshl_b64 s[12:13], s[8:9], 13
	s_add_u32 s12, s52, s12
	s_addc_u32 s13, s53, s13
	v_lshl_add_u64 v[4:5], s[12:13], 0, v[2:3]
	s_ashr_i32 s87, s86, 31
	v_lshl_add_u64 v[24:25], v[22:23], 0, s[10:11]
	v_lshl_add_u64 v[32:33], v[4:5], 0, s[10:11]
	s_lshl_b64 s[10:11], s[86:87], 13
	s_lshl_b64 s[12:13], s[8:9], 12
	s_add_u32 s12, s0, s12
	v_lshlrev_b32_e32 v2, 3, v37
	s_addc_u32 s13, s1, s13
	v_lshl_add_u64 v[2:3], s[12:13], 0, v[2:3]
	s_mov_b64 s[12:13], 0x17400000
	v_lshl_add_u64 v[34:35], v[2:3], 0, s[12:13]
	s_lshl_b64 s[12:13], s[86:87], 12
	s_brev_b32 s9, 64
	global_load_dwordx4 v[104:107], v[22:23], off
	global_load_dwordx4 v[108:111], v[22:23], off offset:1024
	global_load_dwordx4 v[112:115], v[22:23], off offset:2048
	global_load_dwordx4 v[116:119], v[22:23], off offset:3072
	global_load_dwordx4 v[120:123], v[24:25], off
	global_load_dwordx4 v[124:127], v[26:27], off
	global_load_dwordx4 v[128:131], v[28:29], off
	global_load_dwordx4 v[132:135], v[30:31], off
	global_load_dwordx4 v[208:211], v[32:33], off offset:-4096
	global_load_dwordx4 v[212:215], v[32:33], off offset:-3072
	global_load_dwordx4 v[216:219], v[32:33], off offset:-2048
	global_load_dwordx4 v[220:223], v[32:33], off offset:-1024
	global_load_dwordx4 v[224:227], v[32:33], off
	global_load_dwordx4 v[228:231], v[32:33], off offset:1024
	global_load_dwordx4 v[232:235], v[32:33], off offset:2048
	global_load_dwordx4 v[236:239], v[32:33], off offset:3072
	s_waitcnt vmcnt(0)
.LBB0_56:
	s_waitcnt vmcnt(16)
	v_mov_b32_e32 v46, v208
	v_mov_b32_e32 v47, v209
	v_mov_b32_e32 v48, v210
	v_mov_b32_e32 v49, v211
	v_mov_b32_e32 v50, v212
	v_mov_b32_e32 v51, v213
	v_mov_b32_e32 v52, v214
	v_mov_b32_e32 v53, v215
	v_mov_b32_e32 v54, v216
	v_mov_b32_e32 v55, v217
	v_mov_b32_e32 v56, v218
	v_mov_b32_e32 v57, v219
	v_mov_b32_e32 v18, v220
	v_mov_b32_e32 v19, v221
	v_mov_b32_e32 v20, v222
	v_mov_b32_e32 v21, v223
	v_mov_b32_e32 v14, v224
	v_mov_b32_e32 v15, v225
	v_mov_b32_e32 v16, v226
	v_mov_b32_e32 v17, v227
	v_mov_b32_e32 v10, v228
	v_mov_b32_e32 v11, v229
	v_mov_b32_e32 v12, v230
	v_mov_b32_e32 v13, v231
	v_mov_b32_e32 v6, v232
	v_mov_b32_e32 v7, v233
	v_mov_b32_e32 v8, v234
	v_mov_b32_e32 v9, v235
	v_mov_b32_e32 v2, v236
	v_mov_b32_e32 v3, v237
	v_mov_b32_e32 v4, v238
	v_mov_b32_e32 v5, v239
	v_add_co_u32_e32 v58, vcc, s9, v34
	s_add_i32 s14, s14, s86
	s_nop 0
	v_addc_co_u32_e32 v59, vcc, 0, v35, vcc
	v_lshl_add_u64 v[32:33], v[32:33], 0, s[10:11]
	s_cmpk_gt_i32 s14, 0x1fff
	s_cbranch_scc1 .Lmy_n0_skip
	global_load_dwordx4 v[208:211], v[32:33], off offset:-4096
	global_load_dwordx4 v[212:215], v[32:33], off offset:-3072
	global_load_dwordx4 v[216:219], v[32:33], off offset:-2048
	global_load_dwordx4 v[220:223], v[32:33], off offset:-1024
	global_load_dwordx4 v[224:227], v[32:33], off
	global_load_dwordx4 v[228:231], v[32:33], off offset:1024
	global_load_dwordx4 v[232:235], v[32:33], off offset:2048
	global_load_dwordx4 v[236:239], v[32:33], off offset:3072
.Lmy_n0_skip:
	v_cvt_pk_bf16_f32 v60, v46, v47
	v_cvt_pk_bf16_f32 v61, v48, v49
	v_cvt_pk_bf16_f32 v62, v50, v51
	v_cvt_pk_bf16_f32 v63, v52, v53
	v_cvt_pk_bf16_f32 v64, v54, v55
	v_cvt_pk_bf16_f32 v65, v56, v57
	v_cvt_pk_bf16_f32 v66, v18, v19
	v_cvt_pk_bf16_f32 v67, v20, v21
	v_cvt_pk_bf16_f32 v68, v14, v15
	v_cvt_pk_bf16_f32 v69, v16, v17
	v_cvt_pk_bf16_f32 v70, v10, v11
	v_cvt_pk_bf16_f32 v71, v12, v13
	v_cvt_pk_bf16_f32 v72, v6, v7
	v_cvt_pk_bf16_f32 v73, v8, v9
	v_cvt_pk_bf16_f32 v74, v2, v3
	v_cvt_pk_bf16_f32 v75, v4, v5
	global_store_dwordx2 v[58:59], v[60:61], off
	global_store_dwordx2 v[58:59], v[62:63], off offset:512
	global_store_dwordx2 v[58:59], v[64:65], off offset:1024
	global_store_dwordx2 v[58:59], v[66:67], off offset:1536
	global_store_dwordx2 v[58:59], v[68:69], off offset:2048
	global_store_dwordx2 v[58:59], v[70:71], off offset:2560
	global_store_dwordx2 v[58:59], v[72:73], off offset:3072
	global_store_dwordx2 v[58:59], v[74:75], off offset:3584
	v_mov_b32_e32 v58, v104
	v_mov_b32_e32 v59, v105
	v_mov_b32_e32 v60, v106
	v_mov_b32_e32 v61, v107
	v_mov_b32_e32 v78, v47
	v_mov_b32_e32 v79, v51
	v_mov_b32_e32 v82, v49
	v_mov_b32_e32 v83, v53
	v_mov_b32_e32 v76, v46
	v_mov_b32_e32 v77, v50
	v_mov_b32_e32 v80, v48
	v_mov_b32_e32 v81, v52
	v_pk_mul_f32 v[84:85], v[56:57], v[56:57]
	v_pk_mul_f32 v[86:87], v[54:55], v[54:55]
	v_pk_mul_f32 v[62:63], v[78:79], v[78:79]
	v_pk_mul_f32 v[64:65], v[82:83], v[82:83]
	v_pk_mov_b32 v[66:67], v[86:87], v[84:85] op_sel:[1,0]
	v_mov_b32_e32 v87, v85
	v_pk_fma_f32 v[62:63], v[76:77], v[76:77], v[62:63]
	v_pk_fma_f32 v[64:65], v[80:81], v[80:81], v[64:65]
	v_mul_f32_e32 v89, v15, v15
	v_mul_f32_e32 v91, v16, v16
	v_mul_f32_e32 v88, v19, v19
	v_mul_f32_e32 v90, v21, v21
	v_pk_add_f32 v[66:67], v[66:67], v[86:87]
	v_pk_add_f32 v[62:63], v[62:63], v[64:65]
	v_mul_f32_e32 v45, v14, v14
	v_mul_f32_e32 v97, v17, v17
	v_pk_fma_f32 v[68:69], v[18:19], v[18:19], v[88:89] op_sel_hi:[1,1,0]
	v_pk_fma_f32 v[70:71], v[20:21], v[20:21], v[90:91] op_sel_hi:[1,1,0]
	v_pk_add_f32 v[64:65], v[66:67], v[66:67] op_sel:[0,1] op_sel_hi:[1,0]
	v_pk_add_f32 v[62:63], v[62:63], v[62:63] op_sel:[0,1] op_sel_hi:[1,0]
	v_pk_mul_f32 v[92:93], v[12:13], v[12:13]
	v_pk_mul_f32 v[94:95], v[10:11], v[10:11]
	v_mov_b32_e32 v69, v91
	v_mov_b32_e32 v71, v97
	v_mov_b32_e32 v65, v89
	v_mov_b32_e32 v63, v45
	v_pk_mov_b32 v[72:73], v[94:95], v[92:93] op_sel:[1,0]
	v_mov_b32_e32 v95, v93
	v_pk_add_f32 v[66:67], v[68:69], v[70:71]
	v_pk_add_f32 v[62:63], v[62:63], v[64:65]
	v_mul_f32_e32 v99, v2, v2
	v_mul_f32_e32 v96, v7, v7
	v_mul_f32_e32 v98, v9, v9
	v_pk_add_f32 v[72:73], v[72:73], v[94:95]
	v_pk_add_f32 v[62:63], v[62:63], v[66:67]
	v_mul_f32_e32 v100, v3, v3
	v_mul_f32_e32 v101, v4, v4
	v_mul_f32_e32 v102, v5, v5
	v_pk_fma_f32 v[74:75], v[6:7], v[6:7], v[96:97] op_sel_hi:[1,1,0]
	v_pk_fma_f32 v[78:79], v[8:9], v[8:9], v[98:99] op_sel_hi:[1,1,0]
	v_pk_add_f32 v[68:69], v[72:73], v[72:73] op_sel:[0,1] op_sel_hi:[1,0]
	v_pk_add_f32 v[62:63], v[62:63], v[62:63] op_sel:[0,1] op_sel_hi:[1,0]
	v_mov_b32_e32 v75, v101
	v_mov_b32_e32 v79, v102
	v_mov_b32_e32 v69, v100
	v_mov_b32_e32 v63, v99
	v_pk_add_f32 v[70:71], v[74:75], v[78:79]
	v_pk_add_f32 v[62:63], v[62:63], v[68:69]
	s_nop 0
	v_pk_add_f32 v[62:63], v[62:63], v[70:71]
	s_nop 0
	v_add_f32_e32 v45, v62, v63
	ds_bpermute_b32 v62, v38, v45
	s_waitcnt lgkmcnt(0)
	v_add_f32_e32 v45, v45, v62
	ds_bpermute_b32 v62, v39, v45
	s_waitcnt lgkmcnt(0)
	v_add_f32_e32 v45, v45, v62
	ds_bpermute_b32 v62, v40, v45
	s_waitcnt lgkmcnt(0)
	v_add_f32_e32 v45, v45, v62
	ds_bpermute_b32 v62, v41, v45
	s_waitcnt lgkmcnt(0)
	v_add_f32_e32 v45, v45, v62
	ds_bpermute_b32 v62, v42, v45
	s_waitcnt lgkmcnt(0)
	v_add_f32_e32 v45, v45, v62
	ds_bpermute_b32 v62, v43, v45
	s_waitcnt lgkmcnt(0)
	v_add_f32_e32 v45, v45, v62
	v_fmamk_f32 v45, v45, 0x3a000000, v44
	v_rsq_f32_e32 v62, v45
	s_nop 0
	v_pk_mul_f32 v[46:47], v[46:47], v[62:63] op_sel_hi:[1,0]
	v_pk_mul_f32 v[48:49], v[48:49], v[62:63] op_sel_hi:[1,0]
	s_nop 0
	v_pk_mul_f32 v[46:47], v[58:59], v[46:47]
	v_pk_mul_f32 v[48:49], v[60:61], v[48:49]
	v_cvt_pk_bf16_f32 v46, v46, v47
	v_cvt_pk_bf16_f32 v47, v48, v49
	global_store_dwordx2 v[34:35], v[46:47], off
	v_mov_b32_e32 v46, v108
	v_mov_b32_e32 v47, v109
	v_mov_b32_e32 v48, v110
	v_mov_b32_e32 v49, v111
	v_pk_mul_f32 v[50:51], v[50:51], v[62:63] op_sel_hi:[1,0]
	v_pk_mul_f32 v[52:53], v[52:53], v[62:63] op_sel_hi:[1,0]
	v_pk_mul_f32 v[18:19], v[18:19], v[62:63] op_sel_hi:[1,0]
	v_pk_mul_f32 v[20:21], v[20:21], v[62:63] op_sel_hi:[1,0]
	v_pk_mul_f32 v[14:15], v[14:15], v[62:63] op_sel_hi:[1,0]
	v_pk_mul_f32 v[16:17], v[16:17], v[62:63] op_sel_hi:[1,0]
	v_pk_mul_f32 v[10:11], v[10:11], v[62:63] op_sel_hi:[1,0]
	v_pk_mul_f32 v[12:13], v[12:13], v[62:63] op_sel_hi:[1,0]
	v_pk_mul_f32 v[6:7], v[6:7], v[62:63] op_sel_hi:[1,0]
	v_pk_mul_f32 v[8:9], v[8:9], v[62:63] op_sel_hi:[1,0]
	v_pk_mul_f32 v[2:3], v[2:3], v[62:63] op_sel_hi:[1,0]
	v_pk_mul_f32 v[4:5], v[4:5], v[62:63] op_sel_hi:[1,0]
	s_nop 0
	v_pk_mul_f32 v[48:49], v[48:49], v[52:53]
	v_pk_mul_f32 v[46:47], v[46:47], v[50:51]
	v_pk_mul_f32 v[50:51], v[54:55], v[62:63] op_sel_hi:[1,0]
	v_cvt_pk_bf16_f32 v46, v46, v47
	v_cvt_pk_bf16_f32 v47, v48, v49
	global_store_dwordx2 v[34:35], v[46:47], off offset:512
	v_mov_b32_e32 v46, v112
	v_mov_b32_e32 v47, v113
	v_mov_b32_e32 v48, v114
	v_mov_b32_e32 v49, v115
	v_pk_mul_f32 v[52:53], v[56:57], v[62:63] op_sel_hi:[1,0]
	s_nop 0
	v_pk_mul_f32 v[46:47], v[46:47], v[50:51]
	v_pk_mul_f32 v[48:49], v[48:49], v[52:53]
	v_cvt_pk_bf16_f32 v46, v46, v47
	v_cvt_pk_bf16_f32 v47, v48, v49
	global_store_dwordx2 v[34:35], v[46:47], off offset:1024
	v_mov_b32_e32 v46, v116
	v_mov_b32_e32 v47, v117
	v_mov_b32_e32 v48, v118
	v_mov_b32_e32 v49, v119
	s_nop 0
	v_pk_mul_f32 v[20:21], v[48:49], v[20:21]
	v_pk_mul_f32 v[18:19], v[46:47], v[18:19]
	s_nop 0
	v_cvt_pk_bf16_f32 v18, v18, v19
	v_cvt_pk_bf16_f32 v19, v20, v21
	global_store_dwordx2 v[34:35], v[18:19], off offset:1536
	v_mov_b32_e32 v18, v120
	v_mov_b32_e32 v19, v121
	v_mov_b32_e32 v20, v122
	v_mov_b32_e32 v21, v123
	s_nop 0
	v_pk_mul_f32 v[16:17], v[16:17], v[20:21]
	v_pk_mul_f32 v[14:15], v[14:15], v[18:19]
	s_nop 0
	v_cvt_pk_bf16_f32 v14, v14, v15
	v_cvt_pk_bf16_f32 v15, v16, v17
	global_store_dwordx2 v[34:35], v[14:15], off offset:2048
	v_mov_b32_e32 v14, v124
	v_mov_b32_e32 v15, v125
	v_mov_b32_e32 v16, v126
	v_mov_b32_e32 v17, v127
	s_nop 0
	v_pk_mul_f32 v[12:13], v[12:13], v[16:17]
	v_pk_mul_f32 v[10:11], v[10:11], v[14:15]
	s_nop 0
	v_cvt_pk_bf16_f32 v10, v10, v11
	v_cvt_pk_bf16_f32 v11, v12, v13
	global_store_dwordx2 v[34:35], v[10:11], off offset:2560
	v_mov_b32_e32 v10, v128
	v_mov_b32_e32 v11, v129
	v_mov_b32_e32 v12, v130
	v_mov_b32_e32 v13, v131
	s_nop 0
	v_pk_mul_f32 v[8:9], v[8:9], v[12:13]
	v_pk_mul_f32 v[6:7], v[6:7], v[10:11]
	s_nop 0
	v_cvt_pk_bf16_f32 v6, v6, v7
	v_cvt_pk_bf16_f32 v7, v8, v9
	global_store_dwordx2 v[34:35], v[6:7], off offset:3072
	v_mov_b32_e32 v6, v132
	v_mov_b32_e32 v7, v133
	v_mov_b32_e32 v8, v134
	v_mov_b32_e32 v9, v135
	s_nop 0
	v_pk_mul_f32 v[4:5], v[4:5], v[8:9]
	v_pk_mul_f32 v[2:3], v[2:3], v[6:7]
	s_nop 0
	v_cvt_pk_bf16_f32 v2, v2, v3
	v_cvt_pk_bf16_f32 v3, v4, v5
	global_store_dwordx2 v[34:35], v[2:3], off offset:3584
	v_lshl_add_u64 v[34:35], v[34:35], 0, s[12:13]
	s_cbranch_scc0 .LBB0_56
.LBB0_57:
	v_readfirstlane_b32 s9, v36
	s_ashr_i32 s9, s9, 6
	s_lshl_b32 s10, s9, 8
	s_ashr_i32 s11, s10, 31
	v_mov_b32_e32 v2, 0x10100
	s_lshl_b64 s[10:11], s[10:11], 1
	v_lshl_or_b32 v6, v37, 2, v2
	s_add_u32 s10, s0, s10
	v_lshrrev_b32_e32 v2, 1, v37
	s_addc_u32 s11, s1, s11
	v_and_b32_e32 v2, 16, v2
	v_mov_b32_e32 v3, 0
	v_lshl_add_u64 v[4:5], s[10:11], 0, v[2:3]
	s_mov_b64 s[10:11], 0x17400000
	v_lshl_add_u64 v[18:19], v[4:5], 0, s[10:11]
	v_and_b32_e32 v4, 15, v36
	v_mul_u32_u24_e32 v5, 0x1010, v4
	s_lshl_b32 s10, s9, 9
	v_add3_u32 v26, s10, v5, v2
	v_bfe_u32 v5, v36, 4, 2
	v_lshrrev_b32_e32 v2, 5, v36
	s_mov_b32 s10, 0xfffffc
	v_ashrrev_i32_e32 v9, 6, v36
	v_and_or_b32 v2, v2, s10, v5
	v_lshlrev_b32_e32 v10, 7, v9
	v_and_b32_e32 v10, 0x80, v10
	v_lshlrev_b32_e32 v11, 8, v2
	v_lshlrev_b32_e32 v2, 2, v4
	v_or3_b32 v4, v11, v10, v2
	v_lshl_add_u64 v[2:3], s[0:1], 0, v[2:3]
	s_mov_b64 s[0:1], 0x26400000
	v_and_b32_e32 v8, 3, v36
	v_lshl_add_u64 v[20:21], v[2:3], 0, s[0:1]
	v_mul_lo_u32 v2, s96, v5
	v_bfe_u32 v7, v37, 2, 3
	s_lshl_b32 s12, s9, 12
	v_lshl_add_u32 v28, v2, 3, v9
	v_mul_lo_u32 v2, s96, v8
	v_add_u32_e32 v27, 0x10100, v4
	s_sub_i32 s10, s8, s9
	s_lshl_b32 s74, s96, 5
	v_lshl_or_b32 v29, v2, 3, v7
	s_lshl_b64 s[76:77], s[86:87], 2
	s_mov_b64 s[0:1], 0
	v_mov_b64_e32 v[22:23], 0x1fff
	s_movk_i32 s11, 0x2000
	v_add_u32_e32 v30, s12, v6
	s_waitcnt vmcnt(0) lgkmcnt(0)
	s_barrier
	s_branch .LBB0_60

.LBB0_60:
	v_cmp_gt_i64_e32 vcc, s[0:1], v[22:23]
	s_mov_b64 s[8:9], -1
	s_cbranch_vccnz .LBB0_59
	v_add_u32_e32 v2, s10, v29
	v_cmp_gt_i32_e32 vcc, s11, v2
	s_nop 1
	v_cndmask_b32_e32 v2, 0, v2, vcc
	v_ashrrev_i32_e32 v3, 31, v2
	v_lshlrev_b64 v[2:3], 12, v[2:3]
	v_lshl_add_u64 v[24:25], v[18:19], 0, v[2:3]
	global_load_dwordx4 v[104:107], v[24:25], off
	global_load_dwordx4 v[108:111], v[24:25], off offset:32
	global_load_dwordx4 v[112:115], v[24:25], off offset:64
	global_load_dwordx4 v[116:119], v[24:25], off offset:96
	global_load_dwordx4 v[120:123], v[24:25], off offset:128
	global_load_dwordx4 v[124:127], v[24:25], off offset:160
	global_load_dwordx4 v[128:131], v[24:25], off offset:192
	global_load_dwordx4 v[132:135], v[24:25], off offset:224
	global_load_dwordx4 v[136:139], v[24:25], off offset:256
	global_load_dwordx4 v[140:143], v[24:25], off offset:288
	global_load_dwordx4 v[144:147], v[24:25], off offset:320
	global_load_dwordx4 v[148:151], v[24:25], off offset:352
	global_load_dwordx4 v[152:155], v[24:25], off offset:384
	global_load_dwordx4 v[156:159], v[24:25], off offset:416
	global_load_dwordx4 v[200:203], v[24:25], off offset:448
	global_load_dwordx4 v[204:207], v[24:25], off offset:480
	s_nop 0
	ds_read_b128 v[6:9], v26
	ds_read_b128 v[36:39], v26 offset:32
	s_nop 0
	s_waitcnt lgkmcnt(0)
	s_waitcnt vmcnt(15)
	v_mfma_f32_32x32x16_bf16 v[2:17], v[104:107], v[6:9], 0
	s_waitcnt vmcnt(14)
	v_mfma_f32_32x32x16_bf16 v[2:17], v[108:111], v[36:39], v[2:17]
	s_nop 0
	ds_read_b128 v[36:39], v26 offset:64
	ds_read_b128 v[44:47], v26 offset:96
	s_waitcnt lgkmcnt(0)
	s_waitcnt vmcnt(13)
	v_mfma_f32_32x32x16_bf16 v[2:17], v[112:115], v[36:39], v[2:17]
	s_nop 0
	s_nop 0
	s_waitcnt vmcnt(12)
	v_mfma_f32_32x32x16_bf16 v[2:17], v[116:119], v[44:47], v[2:17]
	s_nop 0
	ds_read_b128 v[40:43], v26 offset:128
	ds_read_b128 v[44:47], v26 offset:160
	s_waitcnt lgkmcnt(0)
	s_waitcnt vmcnt(11)
	v_mfma_f32_32x32x16_bf16 v[2:17], v[120:123], v[40:43], v[2:17]
	s_nop 0
	s_nop 0
	s_waitcnt vmcnt(10)
	v_mfma_f32_32x32x16_bf16 v[2:17], v[124:127], v[44:47], v[2:17]
	s_nop 0
	ds_read_b128 v[40:43], v26 offset:192
	ds_read_b128 v[44:47], v26 offset:224
	s_waitcnt lgkmcnt(0)
	s_waitcnt vmcnt(9)
	v_mfma_f32_32x32x16_bf16 v[2:17], v[128:131], v[40:43], v[2:17]
	s_nop 0
	s_nop 0
	s_waitcnt vmcnt(8)
	v_mfma_f32_32x32x16_bf16 v[2:17], v[132:135], v[44:47], v[2:17]
	s_nop 0
	ds_read_b128 v[40:43], v26 offset:256
	ds_read_b128 v[44:47], v26 offset:288
	s_waitcnt lgkmcnt(0)
	s_waitcnt vmcnt(7)
	v_mfma_f32_32x32x16_bf16 v[2:17], v[136:139], v[40:43], v[2:17]
	s_nop 0
	s_nop 0
	s_waitcnt vmcnt(6)
	v_mfma_f32_32x32x16_bf16 v[2:17], v[140:143], v[44:47], v[2:17]
	s_nop 0
	ds_read_b128 v[40:43], v26 offset:320
	ds_read_b128 v[44:47], v26 offset:352
	s_waitcnt lgkmcnt(0)
	s_waitcnt vmcnt(5)
	v_mfma_f32_32x32x16_bf16 v[2:17], v[144:147], v[40:43], v[2:17]
	s_nop 0
	s_nop 0
	s_waitcnt vmcnt(4)
	v_mfma_f32_32x32x16_bf16 v[2:17], v[148:151], v[44:47], v[2:17]
	s_nop 0
	ds_read_b128 v[40:43], v26 offset:384
	ds_read_b128 v[44:47], v26 offset:416
	s_waitcnt lgkmcnt(0)
	s_waitcnt vmcnt(3)
	v_mfma_f32_32x32x16_bf16 v[2:17], v[152:155], v[40:43], v[2:17]
	s_nop 0
	s_nop 0
	s_waitcnt vmcnt(2)
	v_mfma_f32_32x32x16_bf16 v[2:17], v[156:159], v[44:47], v[2:17]
	s_nop 0
	ds_read_b128 v[40:43], v26 offset:448
	ds_read_b128 v[44:47], v26 offset:480
	v_add_u32_e32 v24, s10, v28
	v_cmp_gt_i32_e32 vcc, s11, v24
	s_waitcnt lgkmcnt(0)
	s_waitcnt vmcnt(1)
	v_mfma_f32_32x32x16_bf16 v[2:17], v[200:203], v[40:43], v[2:17]
	s_nop 0
	s_waitcnt vmcnt(0)
	v_mfma_f32_32x32x16_bf16 v[2:17], v[204:207], v[44:47], v[2:17]
	s_nop 11
	ds_write2st64_b32 v30, v2, v3 offset1:1
	ds_write2st64_b32 v30, v4, v5 offset0:2 offset1:3
	ds_write2st64_b32 v30, v6, v7 offset0:4 offset1:5
	ds_write2st64_b32 v30, v8, v9 offset0:6 offset1:7
	ds_write2st64_b32 v30, v10, v11 offset0:8 offset1:9
	ds_write2st64_b32 v30, v12, v13 offset0:10 offset1:11
	ds_write2st64_b32 v30, v14, v15 offset0:12 offset1:13
	ds_write2st64_b32 v30, v16, v17 offset0:14 offset1:15
	s_waitcnt lgkmcnt(0)
	s_barrier
	s_and_saveexec_b64 s[8:9], vcc
	s_cbranch_execz .LBB0_58
	ds_read2st64_b32 v[2:3], v27 offset1:16
	ds_read2st64_b32 v[4:5], v27 offset0:32 offset1:48
	ds_read2st64_b32 v[6:7], v27 offset0:64 offset1:80
	ds_read2st64_b32 v[8:9], v27 offset0:96 offset1:112
	v_ashrrev_i32_e32 v25, 31, v24
	s_waitcnt lgkmcnt(3)
	v_add_f32_e32 v2, 0, v2
	v_add_f32_e32 v2, v2, v3
	s_waitcnt lgkmcnt(2)
	v_add_f32_e32 v2, v2, v4
	v_add_f32_e32 v2, v2, v5
	s_waitcnt lgkmcnt(1)
	v_add_f32_e32 v2, v2, v6
	v_add_f32_e32 v2, v2, v7
	s_waitcnt lgkmcnt(0)
	v_add_f32_e32 v2, v2, v8
	v_add_f32_e32 v4, v2, v9
	v_lshlrev_b64 v[2:3], 6, v[24:25]
	v_lshl_add_u64 v[2:3], v[20:21], 0, v[2:3]
	flat_store_dword v[2:3], v4
	s_branch .LBB0_58

.LBB0_404:
	s_or_b64 exec, exec, s[4:5]
	s_ashr_i32 s4, s8, 6
	v_readlane_b32 s5, v253, 16
	s_add_i32 s4, s4, s5
	s_add_u32 s6, s0, 0x17400000
	s_addc_u32 s7, s1, 0
	s_cmpk_gt_i32 s4, 0x1fff
	v_and_b32_e32 v53, 63, v52
	s_cbranch_scc1 .LBB0_407
	v_and_b32_e32 v0, 64, v236
	v_add_u32_e32 v0, 64, v0
	s_waitcnt lgkmcnt(0)
	v_xor_b32_e32 v1, 1, v236
	v_cmp_lt_i32_e32 vcc, v1, v0
	v_readlane_b32 s8, v254, 31
	v_lshlrev_b32_e32 v160, 4, v53
	v_cndmask_b32_e32 v1, v236, v1, vcc
	v_lshlrev_b32_e32 v54, 2, v1
	v_xor_b32_e32 v1, 2, v236
	v_cmp_lt_i32_e32 vcc, v1, v0
	v_readlane_b32 s9, v254, 32
	s_ashr_i32 s5, s4, 31
	v_cndmask_b32_e32 v1, v236, v1, vcc
	v_lshlrev_b32_e32 v55, 2, v1
	v_xor_b32_e32 v1, 4, v236
	v_cmp_lt_i32_e32 vcc, v1, v0
	v_lshl_add_u64 v[4:5], s[8:9], 0, v[160:161]
	s_mov_b64 s[8:9], 0x1000
	v_cndmask_b32_e32 v1, v236, v1, vcc
	v_lshlrev_b32_e32 v56, 2, v1
	v_xor_b32_e32 v1, 8, v236
	v_cmp_lt_i32_e32 vcc, v1, v0
	v_lshl_add_u64 v[6:7], v[4:5], 0, s[8:9]
	s_mov_b64 s[8:9], 0x1400
	v_cndmask_b32_e32 v1, v236, v1, vcc
	v_lshlrev_b32_e32 v57, 2, v1
	v_xor_b32_e32 v1, 16, v236
	v_cmp_lt_i32_e32 vcc, v1, v0
	v_lshl_add_u64 v[8:9], v[4:5], 0, s[8:9]
	s_mov_b64 s[8:9], 0x1800
	v_cndmask_b32_e32 v1, v236, v1, vcc
	v_lshl_add_u64 v[10:11], v[4:5], 0, s[8:9]
	s_mov_b64 s[8:9], 0x1c00
	v_lshlrev_b32_e32 v58, 2, v1
	v_xor_b32_e32 v1, 32, v236
	v_lshl_add_u64 v[12:13], v[4:5], 0, s[8:9]
	s_lshl_b64 s[8:9], s[4:5], 12
	v_cmp_lt_i32_e32 vcc, v1, v0
	s_add_u32 s8, s6, s8
	v_lshlrev_b32_e32 v160, 3, v53
	v_cndmask_b32_e32 v0, v236, v1, vcc
	s_addc_u32 s9, s7, s9
	v_lshlrev_b32_e32 v59, 2, v0
	v_lshl_add_u64 v[14:15], s[8:9], 0, v[160:161]
	s_mov_b32 s5, s4
	global_load_dwordx4 v[104:107], v[4:5], off
	global_load_dwordx4 v[108:111], v[4:5], off offset:1024
	global_load_dwordx4 v[112:115], v[4:5], off offset:2048
	global_load_dwordx4 v[116:119], v[4:5], off offset:3072
	global_load_dwordx4 v[120:123], v[6:7], off
	global_load_dwordx4 v[124:127], v[8:9], off
	global_load_dwordx4 v[128:131], v[10:11], off
	global_load_dwordx4 v[132:135], v[12:13], off
	v_add_co_u32_e32 v136, vcc, 0x2000000, v14
	s_nop 1
	v_addc_co_u32_e32 v137, vcc, 0, v15, vcc
	global_load_dwordx2 v[140:141], v[136:137], off
	global_load_dwordx2 v[142:143], v[136:137], off offset:512
	global_load_dwordx2 v[144:145], v[136:137], off offset:1024
	global_load_dwordx2 v[146:147], v[136:137], off offset:1536
	global_load_dwordx2 v[148:149], v[136:137], off offset:2048
	global_load_dwordx2 v[150:151], v[136:137], off offset:2560
	global_load_dwordx2 v[152:153], v[136:137], off offset:3072
	global_load_dwordx2 v[154:155], v[136:137], off offset:3584
	s_waitcnt vmcnt(0)
.LBB0_406:
	s_waitcnt vmcnt(8) lgkmcnt(0)
	v_mov_b32_e32 v2, v140
	v_mov_b32_e32 v3, v141
	v_mov_b32_e32 v28, v142
	v_mov_b32_e32 v29, v143
	v_mov_b32_e32 v30, v144
	v_mov_b32_e32 v31, v145
	v_mov_b32_e32 v16, v146
	v_mov_b32_e32 v17, v147
	v_mov_b32_e32 v32, v148
	v_mov_b32_e32 v33, v149
	v_mov_b32_e32 v60, v150
	v_mov_b32_e32 v61, v151
	v_mov_b32_e32 v62, v152
	v_mov_b32_e32 v63, v153
	v_mov_b32_e32 v0, v154
	v_mov_b32_e32 v1, v155
	s_add_i32 s5, s5, s86
	s_cmpk_gt_i32 s5, 0x1fff
	s_cbranch_scc1 .Lmy_n1_skip
	v_lshl_add_u64 v[136:137], v[14:15], 0, s[62:63]
	s_nop 0
	v_add_co_u32_e32 v136, vcc, 0x2000000, v136
	s_nop 1
	v_addc_co_u32_e32 v137, vcc, 0, v137, vcc
	global_load_dwordx2 v[140:141], v[136:137], off
	global_load_dwordx2 v[142:143], v[136:137], off offset:512
	global_load_dwordx2 v[144:145], v[136:137], off offset:1024
	global_load_dwordx2 v[146:147], v[136:137], off offset:1536
	global_load_dwordx2 v[148:149], v[136:137], off offset:2048
	global_load_dwordx2 v[150:151], v[136:137], off offset:2560
	global_load_dwordx2 v[152:153], v[136:137], off offset:3072
	global_load_dwordx2 v[154:155], v[136:137], off offset:3584
.Lmy_n1_skip:
	v_and_b32_e32 v49, 0xffff0000, v2
	v_and_b32_e32 v51, 0xffff0000, v3
	v_lshlrev_b32_e32 v48, 16, v2
	v_lshlrev_b32_e32 v50, 16, v3
	v_lshlrev_b32_e32 v21, 16, v0
	v_and_b32_e32 v19, 0xffff0000, v0
	v_mul_f32_e32 v0, v51, v51
	v_and_b32_e32 v45, 0xffff0000, v29
	v_and_b32_e32 v44, 0xffff0000, v28
	v_mul_f32_e32 v18, v49, v49
	v_lshlrev_b32_e32 v27, 16, v16
	v_and_b32_e32 v25, 0xffff0000, v16
	v_lshlrev_b32_e32 v22, 16, v17
	v_and_b32_e32 v23, 0xffff0000, v17
	v_lshlrev_b32_e32 v16, 16, v1
	v_and_b32_e32 v17, 0xffff0000, v1
	v_pk_fma_f32 v[0:1], v[50:51], v[50:51], v[0:1] op_sel_hi:[1,1,0]
	v_lshlrev_b32_e32 v47, 16, v29
	v_lshlrev_b32_e32 v46, 16, v28
	v_pk_mul_f32 v[2:3], v[44:45], v[44:45]
	v_pk_fma_f32 v[28:29], v[48:49], v[48:49], v[18:19] op_sel_hi:[1,1,0]
	v_pk_fma_f32 v[2:3], v[46:47], v[46:47], v[2:3]
	v_lshlrev_b32_e32 v40, 16, v30
	v_and_b32_e32 v41, 0xffff0000, v30
	v_lshlrev_b32_e32 v42, 16, v31
	v_and_b32_e32 v43, 0xffff0000, v31
	v_mov_b32_e32 v26, v28
	v_mov_b32_e32 v30, v0
	v_mov_b32_e32 v31, v27
	v_mul_f32_e32 v20, v25, v25
	v_pk_add_f32 v[0:1], v[28:29], v[0:1]
	v_pk_mul_f32 v[28:29], v[26:27], v[30:31]
	v_pk_add_f32 v[2:3], v[2:3], v[2:3] op_sel:[0,1] op_sel_hi:[1,0]
	v_mov_b32_e32 v1, v29
	v_mov_b32_e32 v3, v20
	v_pk_add_f32 v[0:1], v[0:1], v[2:3]
	v_mul_f32_e32 v2, v41, v41
	v_mul_f32_e32 v18, v43, v43
	v_mul_f32_e32 v24, v22, v22
	v_mul_f32_e32 v34, v23, v23
	v_pk_fma_f32 v[2:3], v[40:41], v[40:41], v[2:3] op_sel_hi:[1,1,0]
	v_pk_fma_f32 v[28:29], v[42:43], v[42:43], v[18:19] op_sel_hi:[1,1,0]
	v_mov_b32_e32 v3, v24
	v_mov_b32_e32 v29, v34
	v_pk_add_f32 v[2:3], v[2:3], v[28:29]
	v_and_b32_e32 v37, 0xffff0000, v33
	v_and_b32_e32 v36, 0xffff0000, v32
	v_pk_add_f32 v[0:1], v[0:1], v[2:3]
	v_lshlrev_b32_e32 v39, 16, v33
	v_lshlrev_b32_e32 v38, 16, v32
	v_pk_mul_f32 v[2:3], v[36:37], v[36:37]
	v_and_b32_e32 v33, 0xffff0000, v61
	v_pk_fma_f32 v[2:3], v[38:39], v[38:39], v[2:3]
	v_and_b32_e32 v32, 0xffff0000, v60
	v_pk_add_f32 v[2:3], v[2:3], v[2:3] op_sel:[0,1] op_sel_hi:[1,0]
	v_lshlrev_b32_e32 v35, 16, v61
	v_lshlrev_b32_e32 v34, 16, v60
	v_pk_mul_f32 v[28:29], v[32:33], v[32:33]
	v_pk_add_f32 v[0:1], v[0:1], v[0:1] op_sel:[0,1] op_sel_hi:[1,0]
	v_pk_fma_f32 v[60:61], v[34:35], v[34:35], v[28:29]
	v_lshlrev_b32_e32 v28, 16, v62
	v_and_b32_e32 v29, 0xffff0000, v62
	v_lshlrev_b32_e32 v30, 16, v63
	v_and_b32_e32 v31, 0xffff0000, v63
	v_mov_b32_e32 v20, v0
	v_mov_b32_e32 v62, v2
	v_mov_b32_e32 v63, v21
	v_pk_add_f32 v[0:1], v[0:1], v[2:3]
	v_pk_mul_f32 v[2:3], v[20:21], v[62:63]
	v_mul_f32_e32 v18, v19, v19
	v_mov_b32_e32 v1, v3
	v_pk_add_f32 v[2:3], v[60:61], v[60:61] op_sel:[0,1] op_sel_hi:[1,0]
	v_mul_f32_e32 v24, v16, v16
	v_mov_b32_e32 v3, v18
	v_pk_add_f32 v[0:1], v[0:1], v[2:3]
	v_mul_f32_e32 v2, v29, v29
	v_mul_f32_e32 v18, v31, v31
	v_mul_f32_e32 v26, v17, v17
	v_pk_fma_f32 v[2:3], v[28:29], v[28:29], v[2:3] op_sel_hi:[1,1,0]
	v_pk_fma_f32 v[60:61], v[30:31], v[30:31], v[18:19] op_sel_hi:[1,1,0]
	v_mov_b32_e32 v3, v24
	v_mov_b32_e32 v61, v26
	v_pk_add_f32 v[2:3], v[2:3], v[60:61]
	v_mov_b32_e32 v24, v27
	v_pk_add_f32 v[0:1], v[0:1], v[2:3]
	v_mov_b32_e32 v18, v21
	v_add_f32_e32 v0, v0, v1
	ds_bpermute_b32 v1, v54, v0
	s_waitcnt lgkmcnt(0)
	v_add_f32_e32 v0, v0, v1
	ds_bpermute_b32 v1, v55, v0
	s_waitcnt lgkmcnt(0)
	v_add_f32_e32 v0, v0, v1
	ds_bpermute_b32 v1, v56, v0
	s_waitcnt lgkmcnt(0)
	v_add_f32_e32 v0, v0, v1
	ds_bpermute_b32 v1, v57, v0
	s_waitcnt lgkmcnt(0)
	v_add_f32_e32 v0, v0, v1
	ds_bpermute_b32 v1, v58, v0
	s_waitcnt lgkmcnt(0)
	v_add_f32_e32 v0, v0, v1
	ds_bpermute_b32 v1, v59, v0
	s_waitcnt lgkmcnt(0)
	v_add_f32_e32 v0, v0, v1
	v_fmamk_f32 v0, v0, 0x3a000000, v195
	v_rsq_f32_e32 v20, v0
	v_mov_b32_e32 v0, v104
	v_mov_b32_e32 v1, v105
	v_mov_b32_e32 v2, v106
	v_mov_b32_e32 v3, v107
	v_pk_mul_f32 v[48:49], v[20:21], v[48:49] op_sel_hi:[0,1]
	v_pk_mul_f32 v[50:51], v[20:21], v[50:51] op_sel_hi:[0,1]
	v_pk_mul_f32 v[40:41], v[20:21], v[40:41] op_sel_hi:[0,1]
	v_pk_mul_f32 v[42:43], v[20:21], v[42:43] op_sel_hi:[0,1]
	v_pk_mul_f32 v[24:25], v[24:25], v[20:21] op_sel_hi:[1,0]
	v_pk_mul_f32 v[22:23], v[22:23], v[20:21] op_sel_hi:[1,0]
	v_pk_mul_f32 v[18:19], v[18:19], v[20:21] op_sel_hi:[1,0]
	v_pk_mul_f32 v[16:17], v[16:17], v[20:21] op_sel_hi:[1,0]
	s_nop 0
	v_pk_mul_f32 v[2:3], v[2:3], v[50:51]
	v_pk_mul_f32 v[0:1], v[0:1], v[48:49]
	v_mov_b32_e32 v48, v46
	v_cvt_pk_bf16_f32 v0, v0, v1
	v_cvt_pk_bf16_f32 v1, v2, v3
	global_store_dwordx2 v[14:15], v[0:1], off
	v_mov_b32_e32 v0, v108
	v_mov_b32_e32 v1, v109
	v_mov_b32_e32 v2, v110
	v_mov_b32_e32 v3, v111
	v_mov_b32_e32 v49, v44
	v_mov_b32_e32 v44, v47
	v_pk_mul_f32 v[48:49], v[20:21], v[48:49] op_sel_hi:[0,1]
	v_pk_mul_f32 v[44:45], v[20:21], v[44:45] op_sel_hi:[0,1]
	s_nop 0
	v_pk_mul_f32 v[2:3], v[2:3], v[44:45]
	v_pk_mul_f32 v[0:1], v[0:1], v[48:49]
	s_nop 0
	v_cvt_pk_bf16_f32 v0, v0, v1
	v_cvt_pk_bf16_f32 v1, v2, v3
	global_store_dwordx2 v[14:15], v[0:1], off offset:512
	v_mov_b32_e32 v0, v112
	v_mov_b32_e32 v1, v113
	v_mov_b32_e32 v2, v114
	v_mov_b32_e32 v3, v115
	s_nop 0
	v_pk_mul_f32 v[2:3], v[2:3], v[42:43]
	v_pk_mul_f32 v[0:1], v[0:1], v[40:41]
	s_nop 0
	v_cvt_pk_bf16_f32 v0, v0, v1
	v_cvt_pk_bf16_f32 v1, v2, v3
	global_store_dwordx2 v[14:15], v[0:1], off offset:1024
	v_mov_b32_e32 v0, v116
	v_mov_b32_e32 v1, v117
	v_mov_b32_e32 v2, v118
	v_mov_b32_e32 v3, v119
	s_nop 0
	v_pk_mul_f32 v[2:3], v[2:3], v[22:23]
	v_pk_mul_f32 v[0:1], v[0:1], v[24:25]
	v_mov_b32_e32 v22, v38
	v_cvt_pk_bf16_f32 v0, v0, v1
	v_cvt_pk_bf16_f32 v1, v2, v3
	global_store_dwordx2 v[14:15], v[0:1], off offset:1536
	v_mov_b32_e32 v0, v120
	v_mov_b32_e32 v1, v121
	v_mov_b32_e32 v2, v122
	v_mov_b32_e32 v3, v123
	v_mov_b32_e32 v23, v36
	v_mov_b32_e32 v36, v39
	v_pk_mul_f32 v[22:23], v[20:21], v[22:23] op_sel_hi:[0,1]
	v_pk_mul_f32 v[24:25], v[20:21], v[36:37] op_sel_hi:[0,1]
	s_nop 0
	v_pk_mul_f32 v[2:3], v[2:3], v[24:25]
	v_pk_mul_f32 v[0:1], v[0:1], v[22:23]
	v_mov_b32_e32 v22, v34
	v_cvt_pk_bf16_f32 v0, v0, v1
	v_cvt_pk_bf16_f32 v1, v2, v3
	global_store_dwordx2 v[14:15], v[0:1], off offset:2048
	v_mov_b32_e32 v0, v124
	v_mov_b32_e32 v1, v125
	v_mov_b32_e32 v2, v126
	v_mov_b32_e32 v3, v127
	v_mov_b32_e32 v23, v32
	v_mov_b32_e32 v32, v35
	v_pk_mul_f32 v[22:23], v[20:21], v[22:23] op_sel_hi:[0,1]
	v_pk_mul_f32 v[24:25], v[20:21], v[32:33] op_sel_hi:[0,1]
	s_nop 0
	v_pk_mul_f32 v[2:3], v[2:3], v[24:25]
	v_pk_mul_f32 v[0:1], v[0:1], v[22:23]
	v_pk_mul_f32 v[22:23], v[20:21], v[28:29] op_sel_hi:[0,1]
	v_cvt_pk_bf16_f32 v0, v0, v1
	v_cvt_pk_bf16_f32 v1, v2, v3
	global_store_dwordx2 v[14:15], v[0:1], off offset:2560
	v_mov_b32_e32 v0, v128
	v_mov_b32_e32 v1, v129
	v_mov_b32_e32 v2, v130
	v_mov_b32_e32 v3, v131
	v_pk_mul_f32 v[24:25], v[20:21], v[30:31] op_sel_hi:[0,1]
	s_nop 0
	v_pk_mul_f32 v[2:3], v[24:25], v[2:3]
	v_pk_mul_f32 v[0:1], v[22:23], v[0:1]
	s_nop 0
	v_cvt_pk_bf16_f32 v0, v0, v1
	v_cvt_pk_bf16_f32 v1, v2, v3
	global_store_dwordx2 v[14:15], v[0:1], off offset:3072
	v_mov_b32_e32 v0, v132
	v_mov_b32_e32 v1, v133
	v_mov_b32_e32 v2, v134
	v_mov_b32_e32 v3, v135
	s_nop 0
	v_pk_mul_f32 v[2:3], v[16:17], v[2:3]
	v_pk_mul_f32 v[0:1], v[18:19], v[0:1]
	s_nop 0
	v_cvt_pk_bf16_f32 v0, v0, v1
	v_cvt_pk_bf16_f32 v1, v2, v3
	global_store_dwordx2 v[14:15], v[0:1], off offset:3584
	v_lshl_add_u64 v[14:15], v[14:15], 0, s[62:63]
	s_cbranch_scc0 .LBB0_406

.LBB0_410:
	v_mov_b64_e32 v[0:1], 0x1fff
	v_cmp_gt_i64_e32 vcc, s[0:1], v[0:1]
	s_mov_b64 s[4:5], -1
	s_cbranch_vccnz .LBB0_409
	v_add_u32_e32 v0, s6, v22
	v_cmp_gt_i32_e32 vcc, s60, v0
	ds_read_b128 v[4:7], v26
	ds_read_b128 v[32:35], v26 offset:32
	v_cndmask_b32_e32 v0, 0, v0, vcc
	v_ashrrev_i32_e32 v1, 31, v0
	v_lshlrev_b64 v[0:1], 12, v[0:1]
	v_lshl_add_u64 v[24:25], v[16:17], 0, v[0:1]
	global_load_dwordx4 v[64:67], v[24:25], off
	global_load_dwordx4 v[68:71], v[24:25], off offset:32
	global_load_dwordx4 v[72:75], v[24:25], off offset:64
	global_load_dwordx4 v[76:79], v[24:25], off offset:96
	global_load_dwordx4 v[80:83], v[24:25], off offset:128
	global_load_dwordx4 v[84:87], v[24:25], off offset:160
	global_load_dwordx4 v[88:91], v[24:25], off offset:192
	global_load_dwordx4 v[92:95], v[24:25], off offset:224
	global_load_dwordx4 v[96:99], v[24:25], off offset:256
	global_load_dwordx4 v[100:103], v[24:25], off offset:288
	global_load_dwordx4 v[104:107], v[24:25], off offset:320
	global_load_dwordx4 v[108:111], v[24:25], off offset:352
	global_load_dwordx4 v[112:115], v[24:25], off offset:384
	global_load_dwordx4 v[116:119], v[24:25], off offset:416
	global_load_dwordx4 v[120:123], v[24:25], off offset:448
	global_load_dwordx4 v[124:127], v[24:25], off offset:480
	s_nop 0
	s_waitcnt lgkmcnt(0)
	s_waitcnt vmcnt(15)
	v_mfma_f32_32x32x16_bf16 v[0:15], v[64:67], v[4:7], 0
	s_waitcnt vmcnt(14)
	v_mfma_f32_32x32x16_bf16 v[0:15], v[68:71], v[32:35], v[0:15]
	s_nop 0
	ds_read_b128 v[32:35], v26 offset:64
	s_waitcnt lgkmcnt(0)
	s_waitcnt vmcnt(13)
	v_mfma_f32_32x32x16_bf16 v[0:15], v[72:75], v[32:35], v[0:15]
	s_nop 0
	ds_read_b128 v[32:35], v26 offset:96
	s_waitcnt lgkmcnt(0)
	s_waitcnt vmcnt(12)
	v_mfma_f32_32x32x16_bf16 v[0:15], v[76:79], v[32:35], v[0:15]
	s_nop 0
	ds_read_b128 v[32:35], v26 offset:128
	s_waitcnt lgkmcnt(0)
	s_waitcnt vmcnt(11)
	v_mfma_f32_32x32x16_bf16 v[0:15], v[80:83], v[32:35], v[0:15]
	s_nop 0
	ds_read_b128 v[32:35], v26 offset:160
	s_waitcnt lgkmcnt(0)
	s_waitcnt vmcnt(10)
	v_mfma_f32_32x32x16_bf16 v[0:15], v[84:87], v[32:35], v[0:15]
	s_nop 0
	ds_read_b128 v[32:35], v26 offset:192
	s_waitcnt lgkmcnt(0)
	s_waitcnt vmcnt(9)
	v_mfma_f32_32x32x16_bf16 v[0:15], v[88:91], v[32:35], v[0:15]
	s_nop 0
	ds_read_b128 v[32:35], v26 offset:224
	s_waitcnt lgkmcnt(0)
	s_waitcnt vmcnt(8)
	v_mfma_f32_32x32x16_bf16 v[0:15], v[92:95], v[32:35], v[0:15]
	s_nop 0
	ds_read_b128 v[32:35], v26 offset:256
	s_waitcnt lgkmcnt(0)
	s_waitcnt vmcnt(7)
	v_mfma_f32_32x32x16_bf16 v[0:15], v[96:99], v[32:35], v[0:15]
	s_nop 0
	ds_read_b128 v[32:35], v26 offset:288
	s_waitcnt lgkmcnt(0)
	s_waitcnt vmcnt(6)
	v_mfma_f32_32x32x16_bf16 v[0:15], v[100:103], v[32:35], v[0:15]
	s_nop 0
	ds_read_b128 v[32:35], v26 offset:320
	s_waitcnt lgkmcnt(0)
	s_waitcnt vmcnt(5)
	v_mfma_f32_32x32x16_bf16 v[0:15], v[104:107], v[32:35], v[0:15]
	s_nop 0
	ds_read_b128 v[32:35], v26 offset:352
	s_waitcnt lgkmcnt(0)
	s_waitcnt vmcnt(4)
	v_mfma_f32_32x32x16_bf16 v[0:15], v[108:111], v[32:35], v[0:15]
	s_nop 0
	ds_read_b128 v[32:35], v26 offset:384
	s_waitcnt lgkmcnt(0)
	s_waitcnt vmcnt(3)
	v_mfma_f32_32x32x16_bf16 v[0:15], v[112:115], v[32:35], v[0:15]
	s_nop 0
	ds_read_b128 v[32:35], v26 offset:416
	s_waitcnt lgkmcnt(0)
	s_waitcnt vmcnt(2)
	v_mfma_f32_32x32x16_bf16 v[0:15], v[116:119], v[32:35], v[0:15]
	s_nop 0
	ds_read_b128 v[32:35], v26 offset:448
	s_waitcnt lgkmcnt(0)
	s_waitcnt vmcnt(1)
	v_mfma_f32_32x32x16_bf16 v[0:15], v[120:123], v[32:35], v[0:15]
	s_nop 0
	ds_read_b128 v[32:35], v26 offset:480
	v_add_u32_e32 v24, s6, v20
	v_cmp_gt_i32_e32 vcc, s60, v24
	s_waitcnt lgkmcnt(0)
	s_waitcnt vmcnt(0)
	v_mfma_f32_32x32x16_bf16 v[0:15], v[124:127], v[32:35], v[0:15]
	s_nop 11
	ds_write2st64_b32 v21, v0, v1 offset1:1
	ds_write2st64_b32 v21, v2, v3 offset0:2 offset1:3
	ds_write2st64_b32 v21, v4, v5 offset0:4 offset1:5
	ds_write2st64_b32 v21, v6, v7 offset0:6 offset1:7
	ds_write2st64_b32 v21, v8, v9 offset0:8 offset1:9
	ds_write2st64_b32 v21, v10, v11 offset0:10 offset1:11
	ds_write2st64_b32 v21, v12, v13 offset0:12 offset1:13
	ds_write2st64_b32 v21, v14, v15 offset0:14 offset1:15
	s_waitcnt lgkmcnt(0)
	s_barrier
	s_and_saveexec_b64 s[4:5], vcc
	s_cbranch_execz .LBB0_408
	ds_read2st64_b32 v[0:1], v27 offset1:16
	v_ashrrev_i32_e32 v25, 31, v24
	s_waitcnt lgkmcnt(0)
	v_add_f32_e32 v0, 0, v0
	v_add_f32_e32 v2, v0, v1
	ds_read2st64_b32 v[0:1], v27 offset0:32 offset1:48
	s_waitcnt lgkmcnt(0)
	v_add_f32_e32 v0, v2, v0
	v_add_f32_e32 v2, v0, v1
	ds_read2st64_b32 v[0:1], v27 offset0:64 offset1:80
	s_waitcnt lgkmcnt(0)
	v_add_f32_e32 v0, v2, v0
	v_add_f32_e32 v2, v0, v1
	ds_read2st64_b32 v[0:1], v27 offset0:96 offset1:112
	s_waitcnt lgkmcnt(0)
	v_add_f32_e32 v0, v2, v0
	v_add_f32_e32 v2, v0, v1
	v_lshlrev_b64 v[0:1], 6, v[24:25]
	v_lshl_add_u64 v[0:1], v[18:19], 0, v[0:1]
	flat_store_dword v[0:1], v2
	s_branch .LBB0_408
